# c2 + P0 transpose loads de-serialised + SWA epilogue gate rows prefetched after the last head's Q-prep + write-through out stores in the P4 epilogue
# speedup vs baseline: 1.0117x; 1.0067x over previous
.LBB0_11:
	v_lshl_add_u64 v[54:55], v[32:33], 0, s[10:11]
	v_lshl_add_u64 v[56:57], v[30:31], 0, s[10:11]
	v_lshl_add_u64 v[58:59], v[28:29], 0, s[10:11]
	v_lshl_add_u64 v[60:61], v[26:27], 0, s[10:11]
	v_lshl_add_u64 v[62:63], v[24:25], 0, s[10:11]
	v_lshl_add_u64 v[64:65], v[22:23], 0, s[10:11]
	v_lshl_add_u64 v[66:67], v[16:17], 0, s[10:11]
	v_lshl_add_u64 v[68:69], v[14:15], 0, s[10:11]
	global_load_dword v166, v[54:55], off nt
	global_load_dword v167, v[56:57], off nt
	global_load_dword v168, v[58:59], off nt
	global_load_dword v169, v[60:61], off nt
	global_load_dword v170, v[62:63], off nt
	global_load_dword v171, v[64:65], off nt
	global_load_dword v172, v[66:67], off nt
	global_load_dword v173, v[68:69], off nt
	s_add_u32 s10, s10, 0x10000
	s_addc_u32 s11, s11, 0
	v_lshl_add_u64 v[54:55], v[32:33], 0, s[10:11]
	v_lshl_add_u64 v[56:57], v[30:31], 0, s[10:11]
	v_lshl_add_u64 v[58:59], v[28:29], 0, s[10:11]
	v_lshl_add_u64 v[60:61], v[26:27], 0, s[10:11]
	v_lshl_add_u64 v[62:63], v[24:25], 0, s[10:11]
	v_lshl_add_u64 v[64:65], v[22:23], 0, s[10:11]
	v_lshl_add_u64 v[66:67], v[16:17], 0, s[10:11]
	v_lshl_add_u64 v[68:69], v[14:15], 0, s[10:11]
	global_load_dword v174, v[54:55], off nt
	global_load_dword v175, v[56:57], off nt
	global_load_dword v176, v[58:59], off nt
	global_load_dword v177, v[60:61], off nt
	global_load_dword v178, v[62:63], off nt
	global_load_dword v179, v[64:65], off nt
	global_load_dword v180, v[66:67], off nt
	global_load_dword v181, v[68:69], off nt
	s_add_u32 s10, s10, 0x10000
	s_addc_u32 s11, s11, 0
	v_lshl_add_u64 v[54:55], v[32:33], 0, s[10:11]
	v_lshl_add_u64 v[56:57], v[30:31], 0, s[10:11]
	v_lshl_add_u64 v[58:59], v[28:29], 0, s[10:11]
	v_lshl_add_u64 v[60:61], v[26:27], 0, s[10:11]
	v_lshl_add_u64 v[62:63], v[24:25], 0, s[10:11]
	v_lshl_add_u64 v[64:65], v[22:23], 0, s[10:11]
	v_lshl_add_u64 v[66:67], v[16:17], 0, s[10:11]
	v_lshl_add_u64 v[68:69], v[14:15], 0, s[10:11]
	global_load_dword v182, v[54:55], off nt
	global_load_dword v183, v[56:57], off nt
	global_load_dword v184, v[58:59], off nt
	global_load_dword v185, v[60:61], off nt
	global_load_dword v186, v[62:63], off nt
	global_load_dword v248, v[64:65], off nt
	global_load_dword v249, v[66:67], off nt
	global_load_dword v250, v[68:69], off nt
	s_add_u32 s10, s10, 0x10000
	s_addc_u32 s11, s11, 0
	v_lshl_add_u64 v[54:55], v[32:33], 0, s[10:11]
	v_lshl_add_u64 v[56:57], v[30:31], 0, s[10:11]
	v_lshl_add_u64 v[58:59], v[28:29], 0, s[10:11]
	v_lshl_add_u64 v[60:61], v[26:27], 0, s[10:11]
	v_lshl_add_u64 v[62:63], v[24:25], 0, s[10:11]
	v_lshl_add_u64 v[64:65], v[22:23], 0, s[10:11]
	v_lshl_add_u64 v[66:67], v[16:17], 0, s[10:11]
	v_lshl_add_u64 v[68:69], v[14:15], 0, s[10:11]
	global_load_dword v251, v[54:55], off nt
	global_load_dword v252, v[56:57], off nt
	global_load_dword v253, v[58:59], off nt
	global_load_dword v254, v[60:61], off nt
	global_load_dword v255, v[62:63], off nt
	global_load_dword v187, v[64:65], off nt
	global_load_dword v188, v[66:67], off nt
	global_load_dword v189, v[68:69], off nt
	s_add_u32 s10, s10, 0x10000
	s_addc_u32 s11, s11, 0
	v_add_u32_e32 v61, 0x400, v2
	s_waitcnt vmcnt(30)
	ds_write2_b32 v2, v166, v167 offset1:66
	s_waitcnt vmcnt(28)
	ds_write2_b32 v2, v168, v169 offset0:132 offset1:198
	s_waitcnt vmcnt(26)
	ds_write2_b32 v61, v170, v171 offset0:8 offset1:74
	s_waitcnt vmcnt(24)
	ds_write2_b32 v61, v172, v173 offset0:140 offset1:206
	v_add_u32_e32 v2, 0x840, v2
	v_add_u32_e32 v61, 0x400, v2
	s_waitcnt vmcnt(22)
	ds_write2_b32 v2, v174, v175 offset1:66
	s_waitcnt vmcnt(20)
	ds_write2_b32 v2, v176, v177 offset0:132 offset1:198
	s_waitcnt vmcnt(18)
	ds_write2_b32 v61, v178, v179 offset0:8 offset1:74
	s_waitcnt vmcnt(16)
	ds_write2_b32 v61, v180, v181 offset0:140 offset1:206
	v_add_u32_e32 v2, 0x840, v2
	v_add_u32_e32 v61, 0x400, v2
	s_waitcnt vmcnt(14)
	ds_write2_b32 v2, v182, v183 offset1:66
	s_waitcnt vmcnt(12)
	ds_write2_b32 v2, v184, v185 offset0:132 offset1:198
	s_waitcnt vmcnt(10)
	ds_write2_b32 v61, v186, v248 offset0:8 offset1:74
	s_waitcnt vmcnt(8)
	ds_write2_b32 v61, v249, v250 offset0:140 offset1:206
	v_add_u32_e32 v2, 0x840, v2
	v_add_u32_e32 v61, 0x400, v2
	s_waitcnt vmcnt(6)
	ds_write2_b32 v2, v251, v252 offset1:66
	s_waitcnt vmcnt(4)
	ds_write2_b32 v2, v253, v254 offset0:132 offset1:198
	s_waitcnt vmcnt(2)
	ds_write2_b32 v61, v255, v187 offset0:8 offset1:74
	s_waitcnt vmcnt(0)
	ds_write2_b32 v61, v188, v189 offset0:140 offset1:206
	v_add_u32_e32 v2, 0x840, v2
	v_lshl_add_u32 v2, v51, 1, v49
	s_waitcnt lgkmcnt(0)
	v_and_b32_e32 v2, 0x1ffc0, v2
	v_and_b32_e32 v60, 0x3e0, v52
	ds_read2_b32 v[22:23], v34 offset0:33 offset1:41
	ds_read2_b32 v[24:25], v34 offset1:8
	ds_read2_b32 v[26:27], v34 offset0:66 offset1:74
	ds_read2_b32 v[28:29], v34 offset0:99 offset1:107
	ds_read2_b32 v[30:31], v34 offset0:132 offset1:140
	ds_read2_b32 v[32:33], v34 offset0:165 offset1:173
	ds_read2_b32 v[52:53], v34 offset0:198 offset1:206
	ds_read2_b32 v[54:55], v34 offset0:231 offset1:239
	v_lshlrev_b32_e32 v2, 1, v2
	v_lshl_add_u64 v[56:57], v[4:5], 0, v[2:3]
	v_or_b32_e32 v2, v60, v21
	v_lshlrev_b32_e32 v2, 11, v2
	v_lshl_add_u64 v[58:59], v[56:57], 0, v[2:3]
	s_waitcnt lgkmcnt(6)
	v_cvt_pk_bf16_f32 v14, v24, v22
	s_waitcnt lgkmcnt(4)
	v_cvt_pk_bf16_f32 v15, v26, v28
	s_waitcnt lgkmcnt(2)
	v_cvt_pk_bf16_f32 v16, v30, v32
	s_waitcnt lgkmcnt(0)
	v_cvt_pk_bf16_f32 v17, v52, v54
	global_store_dwordx4 v[58:59], v[14:17], off
	v_or_b32_e32 v2, v60, v35
	v_lshlrev_b32_e32 v2, 11, v2
	v_cvt_pk_bf16_f32 v14, v25, v23
	v_cvt_pk_bf16_f32 v15, v27, v29
	v_cvt_pk_bf16_f32 v16, v31, v33
	v_cvt_pk_bf16_f32 v17, v53, v55
	ds_read2_b32 v[24:25], v34 offset0:16 offset1:24
	ds_read2_b32 v[26:27], v34 offset0:49 offset1:57
	ds_read2_b32 v[28:29], v34 offset0:82 offset1:90
	ds_read2_b32 v[30:31], v34 offset0:115 offset1:123
	ds_read2_b32 v[32:33], v34 offset0:148 offset1:156
	ds_read2_b32 v[52:53], v34 offset0:181 offset1:189
	ds_read2_b32 v[54:55], v34 offset0:214 offset1:222
	ds_read2_b32 v[58:59], v34 offset0:247 offset1:255
	v_lshl_add_u64 v[22:23], v[56:57], 0, v[2:3]
	v_or_b32_e32 v2, v60, v36
	v_lshlrev_b32_e32 v2, 11, v2
	global_store_dwordx4 v[22:23], v[14:17], off
	v_lshl_add_u64 v[22:23], v[56:57], 0, v[2:3]
	v_or_b32_e32 v2, v60, v37
	v_lshlrev_b32_e32 v2, 11, v2
	s_waitcnt lgkmcnt(6)
	v_cvt_pk_bf16_f32 v14, v24, v26
	s_waitcnt lgkmcnt(4)
	v_cvt_pk_bf16_f32 v15, v28, v30
	s_waitcnt lgkmcnt(2)
	v_cvt_pk_bf16_f32 v16, v32, v52
	s_waitcnt lgkmcnt(0)
	v_cvt_pk_bf16_f32 v17, v54, v58
	global_store_dwordx4 v[22:23], v[14:17], off
	v_lshl_add_u64 v[22:23], v[56:57], 0, v[2:3]
	s_nop 0
	v_cvt_pk_bf16_f32 v14, v25, v27
	v_cvt_pk_bf16_f32 v15, v29, v31
	v_cvt_pk_bf16_f32 v16, v33, v53
	v_cvt_pk_bf16_f32 v17, v55, v59
	global_store_dwordx4 v[22:23], v[14:17], off
	s_waitcnt lgkmcnt(0)

.LBB0_15:
	v_lshl_add_u64 v[54:55], v[32:33], 0, s[10:11]
	v_lshl_add_u64 v[56:57], v[30:31], 0, s[10:11]
	v_lshl_add_u64 v[58:59], v[28:29], 0, s[10:11]
	v_lshl_add_u64 v[60:61], v[26:27], 0, s[10:11]
	v_lshl_add_u64 v[62:63], v[24:25], 0, s[10:11]
	v_lshl_add_u64 v[64:65], v[22:23], 0, s[10:11]
	v_lshl_add_u64 v[66:67], v[16:17], 0, s[10:11]
	v_lshl_add_u64 v[68:69], v[14:15], 0, s[10:11]
	global_load_dword v166, v[54:55], off nt
	global_load_dword v167, v[56:57], off nt
	global_load_dword v168, v[58:59], off nt
	global_load_dword v169, v[60:61], off nt
	global_load_dword v170, v[62:63], off nt
	global_load_dword v171, v[64:65], off nt
	global_load_dword v172, v[66:67], off nt
	global_load_dword v173, v[68:69], off nt
	s_add_u32 s10, s10, 0x8000
	s_addc_u32 s11, s11, 0
	v_lshl_add_u64 v[54:55], v[32:33], 0, s[10:11]
	v_lshl_add_u64 v[56:57], v[30:31], 0, s[10:11]
	v_lshl_add_u64 v[58:59], v[28:29], 0, s[10:11]
	v_lshl_add_u64 v[60:61], v[26:27], 0, s[10:11]
	v_lshl_add_u64 v[62:63], v[24:25], 0, s[10:11]
	v_lshl_add_u64 v[64:65], v[22:23], 0, s[10:11]
	v_lshl_add_u64 v[66:67], v[16:17], 0, s[10:11]
	v_lshl_add_u64 v[68:69], v[14:15], 0, s[10:11]
	global_load_dword v174, v[54:55], off nt
	global_load_dword v175, v[56:57], off nt
	global_load_dword v176, v[58:59], off nt
	global_load_dword v177, v[60:61], off nt
	global_load_dword v178, v[62:63], off nt
	global_load_dword v179, v[64:65], off nt
	global_load_dword v180, v[66:67], off nt
	global_load_dword v181, v[68:69], off nt
	s_add_u32 s10, s10, 0x8000
	s_addc_u32 s11, s11, 0
	v_lshl_add_u64 v[54:55], v[32:33], 0, s[10:11]
	v_lshl_add_u64 v[56:57], v[30:31], 0, s[10:11]
	v_lshl_add_u64 v[58:59], v[28:29], 0, s[10:11]
	v_lshl_add_u64 v[60:61], v[26:27], 0, s[10:11]
	v_lshl_add_u64 v[62:63], v[24:25], 0, s[10:11]
	v_lshl_add_u64 v[64:65], v[22:23], 0, s[10:11]
	v_lshl_add_u64 v[66:67], v[16:17], 0, s[10:11]
	v_lshl_add_u64 v[68:69], v[14:15], 0, s[10:11]
	global_load_dword v182, v[54:55], off nt
	global_load_dword v183, v[56:57], off nt
	global_load_dword v184, v[58:59], off nt
	global_load_dword v185, v[60:61], off nt
	global_load_dword v186, v[62:63], off nt
	global_load_dword v248, v[64:65], off nt
	global_load_dword v249, v[66:67], off nt
	global_load_dword v250, v[68:69], off nt
	s_add_u32 s10, s10, 0x8000
	s_addc_u32 s11, s11, 0
	v_lshl_add_u64 v[54:55], v[32:33], 0, s[10:11]
	v_lshl_add_u64 v[56:57], v[30:31], 0, s[10:11]
	v_lshl_add_u64 v[58:59], v[28:29], 0, s[10:11]
	v_lshl_add_u64 v[60:61], v[26:27], 0, s[10:11]
	v_lshl_add_u64 v[62:63], v[24:25], 0, s[10:11]
	v_lshl_add_u64 v[64:65], v[22:23], 0, s[10:11]
	v_lshl_add_u64 v[66:67], v[16:17], 0, s[10:11]
	v_lshl_add_u64 v[68:69], v[14:15], 0, s[10:11]
	global_load_dword v251, v[54:55], off nt
	global_load_dword v252, v[56:57], off nt
	global_load_dword v253, v[58:59], off nt
	global_load_dword v254, v[60:61], off nt
	global_load_dword v255, v[62:63], off nt
	global_load_dword v187, v[64:65], off nt
	global_load_dword v188, v[66:67], off nt
	global_load_dword v189, v[68:69], off nt
	s_add_u32 s10, s10, 0x8000
	s_addc_u32 s11, s11, 0
	v_add_u32_e32 v62, 0x400, v2
	s_waitcnt vmcnt(30)
	ds_write2_b32 v2, v166, v167 offset1:66
	s_waitcnt vmcnt(28)
	ds_write2_b32 v2, v168, v169 offset0:132 offset1:198
	s_waitcnt vmcnt(26)
	ds_write2_b32 v62, v170, v171 offset0:8 offset1:74
	s_waitcnt vmcnt(24)
	ds_write2_b32 v62, v172, v173 offset0:140 offset1:206
	v_add_u32_e32 v2, 0x840, v2
	v_add_u32_e32 v62, 0x400, v2
	s_waitcnt vmcnt(22)
	ds_write2_b32 v2, v174, v175 offset1:66
	s_waitcnt vmcnt(20)
	ds_write2_b32 v2, v176, v177 offset0:132 offset1:198
	s_waitcnt vmcnt(18)
	ds_write2_b32 v62, v178, v179 offset0:8 offset1:74
	s_waitcnt vmcnt(16)
	ds_write2_b32 v62, v180, v181 offset0:140 offset1:206
	v_add_u32_e32 v2, 0x840, v2
	v_add_u32_e32 v62, 0x400, v2
	s_waitcnt vmcnt(14)
	ds_write2_b32 v2, v182, v183 offset1:66
	s_waitcnt vmcnt(12)
	ds_write2_b32 v2, v184, v185 offset0:132 offset1:198
	s_waitcnt vmcnt(10)
	ds_write2_b32 v62, v186, v248 offset0:8 offset1:74
	s_waitcnt vmcnt(8)
	ds_write2_b32 v62, v249, v250 offset0:140 offset1:206
	v_add_u32_e32 v2, 0x840, v2
	v_add_u32_e32 v62, 0x400, v2
	s_waitcnt vmcnt(6)
	ds_write2_b32 v2, v251, v252 offset1:66
	s_waitcnt vmcnt(4)
	ds_write2_b32 v2, v253, v254 offset0:132 offset1:198
	s_waitcnt vmcnt(2)
	ds_write2_b32 v62, v255, v187 offset0:8 offset1:74
	s_waitcnt vmcnt(0)
	ds_write2_b32 v62, v188, v189 offset0:140 offset1:206
	v_add_u32_e32 v2, 0x840, v2
	v_and_b32_e32 v2, 0x1e0, v52
	s_waitcnt lgkmcnt(0)
	v_add_u32_e32 v60, 0x900, v2
	v_lshlrev_b32_e32 v2, 1, v53
	ds_read2_b32 v[22:23], v34 offset0:33 offset1:41
	ds_read2_b32 v[24:25], v34 offset1:8
	ds_read2_b32 v[26:27], v34 offset0:66 offset1:74
	ds_read2_b32 v[28:29], v34 offset0:99 offset1:107
	ds_read2_b32 v[30:31], v34 offset0:132 offset1:140
	ds_read2_b32 v[32:33], v34 offset0:165 offset1:173
	ds_read2_b32 v[52:53], v34 offset0:198 offset1:206
	ds_read2_b32 v[54:55], v34 offset0:231 offset1:239
	v_lshl_add_u64 v[56:57], v[6:7], 0, v[2:3]
	v_or_b32_e32 v2, v60, v21
	v_lshlrev_b32_e32 v2, 11, v2
	v_lshl_add_u64 v[58:59], v[56:57], 0, v[2:3]
	s_waitcnt lgkmcnt(6)
	v_cvt_pk_bf16_f32 v14, v24, v22
	s_waitcnt lgkmcnt(4)
	v_cvt_pk_bf16_f32 v15, v26, v28
	s_waitcnt lgkmcnt(2)
	v_cvt_pk_bf16_f32 v16, v30, v32
	s_waitcnt lgkmcnt(0)
	v_cvt_pk_bf16_f32 v17, v52, v54
	global_store_dwordx4 v[58:59], v[14:17], off
	v_or_b32_e32 v2, v60, v35
	v_lshlrev_b32_e32 v2, 11, v2
	v_cvt_pk_bf16_f32 v14, v25, v23
	v_cvt_pk_bf16_f32 v15, v27, v29
	v_cvt_pk_bf16_f32 v16, v31, v33
	v_cvt_pk_bf16_f32 v17, v53, v55
	ds_read2_b32 v[24:25], v34 offset0:16 offset1:24
	ds_read2_b32 v[26:27], v34 offset0:49 offset1:57
	ds_read2_b32 v[28:29], v34 offset0:82 offset1:90
	ds_read2_b32 v[30:31], v34 offset0:115 offset1:123
	ds_read2_b32 v[32:33], v34 offset0:148 offset1:156
	ds_read2_b32 v[52:53], v34 offset0:181 offset1:189
	ds_read2_b32 v[54:55], v34 offset0:214 offset1:222
	ds_read2_b32 v[58:59], v34 offset0:247 offset1:255
	v_lshl_add_u64 v[22:23], v[56:57], 0, v[2:3]
	v_or_b32_e32 v2, v60, v36
	v_lshlrev_b32_e32 v2, 11, v2
	global_store_dwordx4 v[22:23], v[14:17], off
	v_lshl_add_u64 v[22:23], v[56:57], 0, v[2:3]
	v_or_b32_e32 v2, v60, v37
	v_lshlrev_b32_e32 v2, 11, v2
	s_waitcnt lgkmcnt(6)
	v_cvt_pk_bf16_f32 v14, v24, v26
	s_waitcnt lgkmcnt(4)
	v_cvt_pk_bf16_f32 v15, v28, v30
	s_waitcnt lgkmcnt(2)
	v_cvt_pk_bf16_f32 v16, v32, v52
	s_waitcnt lgkmcnt(0)
	v_cvt_pk_bf16_f32 v17, v54, v58
	global_store_dwordx4 v[22:23], v[14:17], off
	v_lshl_add_u64 v[22:23], v[56:57], 0, v[2:3]
	s_nop 0
	v_cvt_pk_bf16_f32 v14, v25, v27
	v_cvt_pk_bf16_f32 v15, v29, v31
	v_cvt_pk_bf16_f32 v16, v33, v53
	v_cvt_pk_bf16_f32 v17, v55, v59
	global_store_dwordx4 v[22:23], v[14:17], off
	s_waitcnt lgkmcnt(0)

.LBB0_20:
	v_add_u32_e32 v17, s8, v2
	v_add_u32_e32 v26, 2, v17
	v_add_u32_e32 v28, 4, v17
	v_add_u32_e32 v30, 6, v17
	v_mad_i64_i32 v[24:25], s[10:11], v17, s18, v[22:23]
	v_add_u32_e32 v32, 8, v17
	v_add_u32_e32 v52, 10, v17
	v_add_u32_e32 v54, 12, v17
	v_add_u32_e32 v17, 14, v17
	v_mad_i64_i32 v[26:27], s[10:11], v26, s18, v[22:23]
	v_mad_i64_i32 v[28:29], s[10:11], v28, s18, v[22:23]
	v_mad_i64_i32 v[30:31], s[10:11], v30, s18, v[22:23]
	v_mad_i64_i32 v[32:33], s[10:11], v32, s18, v[22:23]
	v_mad_i64_i32 v[52:53], s[10:11], v52, s18, v[22:23]
	v_mad_i64_i32 v[54:55], s[10:11], v54, s18, v[22:23]
	v_mad_i64_i32 v[56:57], s[10:11], v17, s18, v[22:23]
	global_load_dword v166, v[24:25], off nt
	global_load_dword v167, v[26:27], off nt
	global_load_dword v168, v[28:29], off nt
	global_load_dword v169, v[30:31], off nt
	global_load_dword v170, v[32:33], off nt
	global_load_dword v171, v[52:53], off nt
	global_load_dword v172, v[54:55], off nt
	global_load_dword v173, v[56:57], off nt
	s_add_i32 s8, s8, 16
	v_add_u32_e32 v17, s8, v2
	v_add_u32_e32 v26, 2, v17
	v_add_u32_e32 v28, 4, v17
	v_add_u32_e32 v30, 6, v17
	v_mad_i64_i32 v[24:25], s[10:11], v17, s18, v[22:23]
	v_add_u32_e32 v32, 8, v17
	v_add_u32_e32 v52, 10, v17
	v_add_u32_e32 v54, 12, v17
	v_add_u32_e32 v17, 14, v17
	v_mad_i64_i32 v[26:27], s[10:11], v26, s18, v[22:23]
	v_mad_i64_i32 v[28:29], s[10:11], v28, s18, v[22:23]
	v_mad_i64_i32 v[30:31], s[10:11], v30, s18, v[22:23]
	v_mad_i64_i32 v[32:33], s[10:11], v32, s18, v[22:23]
	v_mad_i64_i32 v[52:53], s[10:11], v52, s18, v[22:23]
	v_mad_i64_i32 v[54:55], s[10:11], v54, s18, v[22:23]
	v_mad_i64_i32 v[56:57], s[10:11], v17, s18, v[22:23]
	global_load_dword v174, v[24:25], off nt
	global_load_dword v175, v[26:27], off nt
	global_load_dword v176, v[28:29], off nt
	global_load_dword v177, v[30:31], off nt
	global_load_dword v178, v[32:33], off nt
	global_load_dword v179, v[52:53], off nt
	global_load_dword v180, v[54:55], off nt
	global_load_dword v181, v[56:57], off nt
	s_add_i32 s8, s8, 16
	v_add_u32_e32 v17, s8, v2
	v_add_u32_e32 v26, 2, v17
	v_add_u32_e32 v28, 4, v17
	v_add_u32_e32 v30, 6, v17
	v_mad_i64_i32 v[24:25], s[10:11], v17, s18, v[22:23]
	v_add_u32_e32 v32, 8, v17
	v_add_u32_e32 v52, 10, v17
	v_add_u32_e32 v54, 12, v17
	v_add_u32_e32 v17, 14, v17
	v_mad_i64_i32 v[26:27], s[10:11], v26, s18, v[22:23]
	v_mad_i64_i32 v[28:29], s[10:11], v28, s18, v[22:23]
	v_mad_i64_i32 v[30:31], s[10:11], v30, s18, v[22:23]
	v_mad_i64_i32 v[32:33], s[10:11], v32, s18, v[22:23]
	v_mad_i64_i32 v[52:53], s[10:11], v52, s18, v[22:23]
	v_mad_i64_i32 v[54:55], s[10:11], v54, s18, v[22:23]
	v_mad_i64_i32 v[56:57], s[10:11], v17, s18, v[22:23]
	global_load_dword v182, v[24:25], off nt
	global_load_dword v183, v[26:27], off nt
	global_load_dword v184, v[28:29], off nt
	global_load_dword v185, v[30:31], off nt
	global_load_dword v186, v[32:33], off nt
	global_load_dword v248, v[52:53], off nt
	global_load_dword v249, v[54:55], off nt
	global_load_dword v250, v[56:57], off nt
	s_add_i32 s8, s8, 16
	v_add_u32_e32 v17, s8, v2
	v_add_u32_e32 v26, 2, v17
	v_add_u32_e32 v28, 4, v17
	v_add_u32_e32 v30, 6, v17
	v_mad_i64_i32 v[24:25], s[10:11], v17, s18, v[22:23]
	v_add_u32_e32 v32, 8, v17
	v_add_u32_e32 v52, 10, v17
	v_add_u32_e32 v54, 12, v17
	v_add_u32_e32 v17, 14, v17
	v_mad_i64_i32 v[26:27], s[10:11], v26, s18, v[22:23]
	v_mad_i64_i32 v[28:29], s[10:11], v28, s18, v[22:23]
	v_mad_i64_i32 v[30:31], s[10:11], v30, s18, v[22:23]
	v_mad_i64_i32 v[32:33], s[10:11], v32, s18, v[22:23]
	v_mad_i64_i32 v[52:53], s[10:11], v52, s18, v[22:23]
	v_mad_i64_i32 v[54:55], s[10:11], v54, s18, v[22:23]
	v_mad_i64_i32 v[56:57], s[10:11], v17, s18, v[22:23]
	global_load_dword v251, v[24:25], off nt
	global_load_dword v252, v[26:27], off nt
	global_load_dword v253, v[28:29], off nt
	global_load_dword v254, v[30:31], off nt
	global_load_dword v255, v[32:33], off nt
	global_load_dword v187, v[52:53], off nt
	global_load_dword v188, v[54:55], off nt
	global_load_dword v189, v[56:57], off nt
	s_add_i32 s8, s8, 16
	v_add_u32_e32 v31, 0x400, v15
	s_waitcnt vmcnt(30)
	ds_write2_b32 v15, v166, v167 offset1:66
	s_waitcnt vmcnt(28)
	ds_write2_b32 v15, v168, v169 offset0:132 offset1:198
	s_waitcnt vmcnt(26)
	ds_write2_b32 v31, v170, v171 offset0:8 offset1:74
	s_waitcnt vmcnt(24)
	ds_write2_b32 v31, v172, v173 offset0:140 offset1:206
	v_add_u32_e32 v15, 0x840, v15
	v_add_u32_e32 v31, 0x400, v15
	s_waitcnt vmcnt(22)
	ds_write2_b32 v15, v174, v175 offset1:66
	s_waitcnt vmcnt(20)
	ds_write2_b32 v15, v176, v177 offset0:132 offset1:198
	s_waitcnt vmcnt(18)
	ds_write2_b32 v31, v178, v179 offset0:8 offset1:74
	s_waitcnt vmcnt(16)
	ds_write2_b32 v31, v180, v181 offset0:140 offset1:206
	v_add_u32_e32 v15, 0x840, v15
	v_add_u32_e32 v31, 0x400, v15
	s_waitcnt vmcnt(14)
	ds_write2_b32 v15, v182, v183 offset1:66
	s_waitcnt vmcnt(12)
	ds_write2_b32 v15, v184, v185 offset0:132 offset1:198
	s_waitcnt vmcnt(10)
	ds_write2_b32 v31, v186, v248 offset0:8 offset1:74
	s_waitcnt vmcnt(8)
	ds_write2_b32 v31, v249, v250 offset0:140 offset1:206
	v_add_u32_e32 v15, 0x840, v15
	v_add_u32_e32 v31, 0x400, v15
	s_waitcnt vmcnt(6)
	ds_write2_b32 v15, v251, v252 offset1:66
	s_waitcnt vmcnt(4)
	ds_write2_b32 v15, v253, v254 offset0:132 offset1:198
	s_waitcnt vmcnt(2)
	ds_write2_b32 v31, v255, v187 offset0:8 offset1:74
	s_waitcnt vmcnt(0)
	ds_write2_b32 v31, v188, v189 offset0:140 offset1:206
	v_add_u32_e32 v15, 0x840, v15
	s_waitcnt lgkmcnt(0)
	ds_read2_b32 v[26:27], v34 offset0:33 offset1:41
	ds_read2_b32 v[28:29], v34 offset1:8
	ds_read2_b32 v[30:31], v34 offset0:66 offset1:74
	ds_read2_b32 v[32:33], v34 offset0:99 offset1:107
	ds_read2_b32 v[52:53], v34 offset0:132 offset1:140
	ds_read2_b32 v[54:55], v34 offset0:165 offset1:173
	ds_read2_b32 v[56:57], v34 offset0:198 offset1:206
	ds_read2_b32 v[58:59], v34 offset0:231 offset1:239
	v_or_b32_e32 v60, v14, v21
	v_ashrrev_i32_e32 v17, 31, v16
	v_ashrrev_i32_e32 v61, 31, v60
	v_lshl_add_u64 v[16:17], v[16:17], 1, v[6:7]
	v_lshlrev_b64 v[60:61], 11, v[60:61]
	s_waitcnt lgkmcnt(6)
	v_cvt_pk_bf16_f32 v22, v28, v26
	v_lshl_add_u64 v[60:61], v[16:17], 0, v[60:61]
	v_or_b32_e32 v26, v14, v35
	s_waitcnt lgkmcnt(4)
	v_cvt_pk_bf16_f32 v23, v30, v32
	s_waitcnt lgkmcnt(2)
	v_cvt_pk_bf16_f32 v24, v52, v54
	s_waitcnt lgkmcnt(0)
	v_cvt_pk_bf16_f32 v25, v56, v58
	global_store_dwordx4 v[60:61], v[22:25], off
	s_nop 1
	v_cvt_pk_bf16_f32 v22, v29, v27
	v_ashrrev_i32_e32 v27, 31, v26
	v_cvt_pk_bf16_f32 v23, v31, v33
	v_cvt_pk_bf16_f32 v24, v53, v55
	v_cvt_pk_bf16_f32 v25, v57, v59
	v_lshlrev_b64 v[26:27], 11, v[26:27]
	ds_read2_b32 v[28:29], v34 offset0:16 offset1:24
	ds_read2_b32 v[30:31], v34 offset0:49 offset1:57
	ds_read2_b32 v[32:33], v34 offset0:82 offset1:90
	ds_read2_b32 v[52:53], v34 offset0:115 offset1:123
	ds_read2_b32 v[54:55], v34 offset0:148 offset1:156
	ds_read2_b32 v[56:57], v34 offset0:181 offset1:189
	ds_read2_b32 v[58:59], v34 offset0:214 offset1:222
	ds_read2_b32 v[60:61], v34 offset0:247 offset1:255
	v_lshl_add_u64 v[26:27], v[16:17], 0, v[26:27]
	global_store_dwordx4 v[26:27], v[22:25], off
	v_or_b32_e32 v26, v14, v36
	v_or_b32_e32 v14, v14, v37
	v_ashrrev_i32_e32 v27, 31, v26
	v_ashrrev_i32_e32 v15, 31, v14
	v_lshlrev_b64 v[26:27], 11, v[26:27]
	v_lshlrev_b64 v[14:15], 11, v[14:15]
	s_waitcnt lgkmcnt(6)
	v_cvt_pk_bf16_f32 v22, v28, v30
	s_waitcnt lgkmcnt(4)
	v_cvt_pk_bf16_f32 v23, v32, v52
	s_waitcnt lgkmcnt(2)
	v_cvt_pk_bf16_f32 v24, v54, v56
	s_waitcnt lgkmcnt(0)
	v_cvt_pk_bf16_f32 v25, v58, v60
	v_lshl_add_u64 v[26:27], v[16:17], 0, v[26:27]
	v_lshl_add_u64 v[14:15], v[16:17], 0, v[14:15]
	global_store_dwordx4 v[26:27], v[22:25], off
	s_nop 1
	v_cvt_pk_bf16_f32 v22, v29, v31
	v_cvt_pk_bf16_f32 v23, v33, v53
	v_cvt_pk_bf16_f32 v24, v55, v57
	v_cvt_pk_bf16_f32 v25, v59, v61
	global_store_dwordx4 v[14:15], v[22:25], off
	s_waitcnt lgkmcnt(0)
	s_branch .LBB0_7
